# NSA items dequeued heaviest-first across the three head groups (item n -> group n%3, tile 255-n/3) instead of group by group
# speedup vs baseline: 1.0045x; 1.0045x over previous
.LBB0_1057:
	s_andn2_b64 vcc, exec, s[6:7]
	s_cbranch_vccnz .LBB0_1255
	s_add_i32 s6, s24, 0xffffffa0
	s_mul_hi_u32 s7, s6, 0xaaaaaaab
	s_lshr_b32 s7, s7, 1
	s_mul_i32 s10, s7, 3
	s_sub_i32 s6, s6, s10
	s_lshl_b32 s6, s6, 8
	s_or_b32 s6, s6, s7
	v_mov_b32_e32 v218, v203
	s_and_b32 s50, s6, 0xff
	s_xor_b32 s25, s50, 0xff
	v_readfirstlane_b32 s79, v218
	s_ashr_i32 s78, s79, 6
	s_cmp_ge_i32 s78, 4
	s_cbranch_scc0 .Lnsa_prio_skip
	s_setprio 1
